# FFN gate fix-up phase by hand: all 3-4 tasks of a wave loaded together (one memory round trip instead of two per task)
# baseline (speedup 1.0000x reference)
; __device__ __forceinline__ void ffngate_fix(bf16_t* A2, const bf16_t* side, int rows, const float* fk, const float* fb, int gw, int NGW, int lane) {
;     const int ntask = (rows / 64) * 2 * 11;
;     for (int wt = gw; wt < ntask; wt += NGW) {
;         const int s = wt % 11, sw = wt / 11, last = sw & 1, G = sw >> 1, ch = 256 * s + 4 * lane;
;         const int R = 64 * G + (last ? 63 : 0);
;         const bool lat = R < ML; const int t = lat ? (R & (SEQ - 1)) : ((R - ML) & (CL - 1)); const int L = lat ? SEQ : CL;
;         const bool hasp = t > 0, hasn = t < L - 1;
;         const bf16_t* pc = side + (size_t)(G * 4 + (last ? 3 : 0)) * DFF2 + ch;
;         const bf16_t* pp = last ? side + (size_t)(G * 4 + 2) * DFF2 + ch : side + (size_t)((G - 1) * 4 + 3) * DFF2 + ch;
;         const bf16_t* pn = last ? side + (size_t)((G + 1) * 4 + 0) * DFF2 + ch : side + (size_t)(G * 4 + 1) * DFF2 + ch;
;         u32x2 cv = *(const u32x2*)pc, cg = *(const u32x2*)(pc + DFF), pv = (u32x2){0u, 0u}, pg = pv, nv = pv, ng = pv;
;         if (hasp) { pv = *(const u32x2*)pp; pg = *(const u32x2*)(pp + DFF); }
;         if (hasn) { nv = *(const u32x2*)pn; ng = *(const u32x2*)(pn + DFF); }
;         const f32x4 kv0 = *(const f32x4*)(fk + ch), kv1 = *(const f32x4*)(fk + DFF2 + ch), kv2 = *(const f32x4*)(fk + 2 * DFF2 + ch), bv = *(const f32x4*)(fb + ch);
;         const f32x4 kg0 = *(const f32x4*)(fk + DFF + ch), kg1 = *(const f32x4*)(fk + DFF2 + DFF + ch), kg2 = *(const f32x4*)(fk + 2 * DFF2 + DFF + ch), bg = *(const f32x4*)(fb + DFF + ch);
.LBB0_118:
	s_ashr_i32 s73, s72, 31
	s_add_u32 s10, s54, 0x7000000
	v_writelane_b32 v254, s38, 34
	s_addc_u32 s11, s55, 0
	v_writelane_b32 v254, s10, 35
	s_nop 1
	v_writelane_b32 v254, s11, 36
	s_add_u32 s10, s54, 0x9400000
	s_addc_u32 s11, s55, 0
	v_writelane_b32 v254, s10, 37
	s_nop 1
	v_writelane_b32 v254, s11, 38
	s_add_u32 s10, s54, 0x15400000
	s_addc_u32 s11, s55, 0
	v_writelane_b32 v254, s10, 39
	s_add_u32 s1, s54, 0x16000000
	s_nop 0
	v_writelane_b32 v254, s11, 40
	v_writelane_b32 v254, s1, 41
	s_addc_u32 s1, s55, 0
	v_writelane_b32 v254, s1, 42
	v_writelane_b32 v254, s29, 43
	v_writelane_b32 v254, s34, 44
	v_writelane_b32 v254, s92, 45
	s_cmp_lg_u32 s0, 2
	s_mov_b64 s[10:11], -1
	v_writelane_b32 v254, s93, 46
	v_writelane_b32 v254, s68, 47
	s_nop 1
	v_writelane_b32 v254, s69, 48
	s_cbranch_scc0 .LBB0_908
	s_and_b64 vcc, exec, s[8:9]
	s_cbranch_vccz .LBB0_811
	s_mov_b64 s[8:9], -1
	s_and_b64 vcc, exec, s[6:7]
	v_writelane_b32 v254, s65, 51
	s_cbranch_vccz .LBB0_590
	s_mov_b64 s[6:7], 0
	s_cmp_lt_i32 s0, 7
	s_mov_b64 s[8:9], 0
	v_readlane_b32 s45, v254, 41
	v_readlane_b32 s46, v254, 42
	s_cbranch_scc1 .LBB0_134
	s_cmp_eq_u32 s0, 7
	s_mov_b64 s[8:9], -1
	s_cbranch_scc0 .LBB0_133
	s_lshr_b32 s1, s65, 5
	s_mul_i32 s1, s1, 11
	v_readlane_b32 s8, v254, 28
	v_mov_b32_e32 v0, v196
	s_cmp_ge_i32 s8, s1
	v_readlane_b32 s9, v254, 29
	s_cbranch_scc1 .LBB0_132
	s_load_dwordx4 s[8:11], s[62:63], 0xa0
	v_readlane_b32 s27, v254, 28
	v_readlane_b32 s36, v254, 37
	v_readlane_b32 s37, v254, 38
	v_and_b32_e32 v1, 63, v196
	v_lshlrev_b32_e32 v3, 4, v1
	v_lshlrev_b32_e32 v1, 3, v1
	v_add_u32_e32 v2, 0x1600, v1
	v_add_u32_e32 v4, 0x2c00, v3
	v_add_u32_e32 v5, 0x5800, v3
	v_add_u32_e32 v6, 0x8400, v3
	v_add_u32_e32 v7, 0xb000, v3
	v_add_u32_e32 v8, 0xdc00, v3
	s_mov_b32 s3, 0xffff0000
	s_mul_i32 s29, s72, 0x10800
	s_mul_i32 s30, s72, 0x5800
	s_waitcnt lgkmcnt(0)
	s_add_u32 s8, s8, s29
	s_addc_u32 s9, s9, 0
	s_add_u32 s10, s10, s30
	s_addc_u32 s11, s11, 0
	s_mov_b32 s22, 0
	s_cmp_lt_u32 s27, s1
	s_cbranch_scc0 .Lgb_ld0
	s_mul_hi_u32 s31, s27, 0xba2e8ba3
	s_lshr_b32 s31, s31, 3
	s_mul_i32 s32, s31, 11
	s_sub_u32 s32, s27, s32
	s_and_b32 s34, s31, 1
	s_lshr_b32 s31, s31, 1
	s_lshl_b32 s38, s31, 6
	s_mul_i32 s40, s34, 63
	s_add_u32 s38, s38, s40
	s_lshl_b32 s41, s31, 2
	s_mul_i32 s40, s34, 3
	s_add_u32 s41, s41, s40
	s_lshl_b32 s32, s32, 9
	s_cmp_lt_u32 s38, 0x4000
	s_movk_i32 s42, 0x7ff
	s_movk_i32 s43, 0xff
	s_cselect_b32 s42, s42, s43
	s_and_b32 s43, s38, s42
	s_mov_b32 s22, 1
	s_cmp_lg_u32 s43, 0
	s_cselect_b32 s44, 2, 0
	s_or_b32 s22, s22, s44
	s_cmp_lg_u32 s43, s42
	s_cselect_b32 s44, 4, 0
	s_or_b32 s22, s22, s44
	s_mul_i32 s44, s38, 0x1600
	s_add_u32 s12, s36, s44
	s_addc_u32 s13, s37, 0
	s_add_u32 s12, s12, s32
	s_addc_u32 s13, s13, 0
	s_mul_i32 s44, s41, 0x2c00
	s_add_u32 s40, s45, s44
	s_addc_u32 s41, s46, 0
	s_add_u32 s40, s40, s32
	s_addc_u32 s41, s41, 0
	s_sub_u32 s42, s40, 0x2c00
	s_subb_u32 s43, s41, 0
	global_load_dwordx2 v[16:17], v1, s[40:41]
	global_load_dwordx2 v[18:19], v2, s[40:41]
	global_load_dwordx2 v[20:21], v1, s[42:43]
	global_load_dwordx2 v[22:23], v2, s[42:43]
	s_add_u32 s42, s40, 0x2c00
	s_addc_u32 s43, s41, 0
	global_load_dwordx2 v[24:25], v1, s[42:43]
	global_load_dwordx2 v[26:27], v2, s[42:43]
	s_lshl_b32 s32, s32, 1
	s_add_u32 s40, s8, s32
	s_addc_u32 s41, s9, 0
	s_add_u32 s42, s10, s32
	s_addc_u32 s43, s11, 0
	global_load_dwordx4 v[28:31], v3, s[40:41]
	global_load_dwordx4 v[32:35], v4, s[40:41]
	global_load_dwordx4 v[36:39], v5, s[40:41]
	global_load_dwordx4 v[40:43], v6, s[40:41]
	global_load_dwordx4 v[44:47], v7, s[40:41]
	global_load_dwordx4 v[48:51], v8, s[40:41]
	global_load_dwordx4 v[52:55], v3, s[42:43]
	global_load_dwordx4 v[56:59], v4, s[42:43]
.Lgb_ld0:
	s_add_u32 s27, s27, s26
	s_mov_b32 s23, 0
	s_cmp_lt_u32 s27, s1
	s_cbranch_scc0 .Lgb_ld1
	s_mul_hi_u32 s31, s27, 0xba2e8ba3
	s_lshr_b32 s31, s31, 3
	s_mul_i32 s32, s31, 11
	s_sub_u32 s32, s27, s32
	s_and_b32 s34, s31, 1
	s_lshr_b32 s31, s31, 1
	s_lshl_b32 s38, s31, 6
	s_mul_i32 s40, s34, 63
	s_add_u32 s38, s38, s40
	s_lshl_b32 s41, s31, 2
	s_mul_i32 s40, s34, 3
	s_add_u32 s41, s41, s40
	s_lshl_b32 s32, s32, 9
	s_cmp_lt_u32 s38, 0x4000
	s_movk_i32 s42, 0x7ff
	s_movk_i32 s43, 0xff
	s_cselect_b32 s42, s42, s43
	s_and_b32 s43, s38, s42
	s_mov_b32 s23, 1
	s_cmp_lg_u32 s43, 0
	s_cselect_b32 s44, 2, 0
	s_or_b32 s23, s23, s44
	s_cmp_lg_u32 s43, s42
	s_cselect_b32 s44, 4, 0
	s_or_b32 s23, s23, s44
	s_mul_i32 s44, s38, 0x1600
	s_add_u32 s14, s36, s44
	s_addc_u32 s15, s37, 0
	s_add_u32 s14, s14, s32
	s_addc_u32 s15, s15, 0
	s_mul_i32 s44, s41, 0x2c00
	s_add_u32 s40, s45, s44
	s_addc_u32 s41, s46, 0
	s_add_u32 s40, s40, s32
	s_addc_u32 s41, s41, 0
	s_sub_u32 s42, s40, 0x2c00
	s_subb_u32 s43, s41, 0
	global_load_dwordx2 v[60:61], v1, s[40:41]
	global_load_dwordx2 v[62:63], v2, s[40:41]
	global_load_dwordx2 v[64:65], v1, s[42:43]
	global_load_dwordx2 v[66:67], v2, s[42:43]
	s_add_u32 s42, s40, 0x2c00
	s_addc_u32 s43, s41, 0
	global_load_dwordx2 v[68:69], v1, s[42:43]
	global_load_dwordx2 v[70:71], v2, s[42:43]
	s_lshl_b32 s32, s32, 1
	s_add_u32 s40, s8, s32
	s_addc_u32 s41, s9, 0
	s_add_u32 s42, s10, s32
	s_addc_u32 s43, s11, 0
	global_load_dwordx4 v[72:75], v3, s[40:41]
	global_load_dwordx4 v[76:79], v4, s[40:41]
	global_load_dwordx4 v[80:83], v5, s[40:41]
	global_load_dwordx4 v[84:87], v6, s[40:41]
	global_load_dwordx4 v[88:91], v7, s[40:41]
	global_load_dwordx4 v[92:95], v8, s[40:41]
	global_load_dwordx4 v[98:101], v3, s[42:43]
	global_load_dwordx4 v[102:105], v4, s[42:43]
; #define UNP(w) (f32x4){bflo((w).x), bfhi((w).x), bflo((w).y), bfhi((w).y)}
; __device__ __forceinline__ void ffngate_fix(bf16_t* A2, const bf16_t* side, int rows, const float* fk, const float* fb, int gw, int NGW, int lane) {
;     ...
;     for (int wt = gw; wt < ntask; wt += NGW) {
;         const int s = wt % 11, sw = wt / 11, last = sw & 1, G = sw >> 1, ch = 256 * s + 4 * lane;
;         const int R = 64 * G + (last ? 63 : 0);
;         const bool lat = R < ML; const int t = lat ? (R & (SEQ - 1)) : ((R - ML) & (CL - 1)); const int L = lat ? SEQ : CL;
;         const bool hasp = t > 0, hasn = t < L - 1;
;         const bf16_t* pc = side + (size_t)(G * 4 + (last ? 3 : 0)) * DFF2 + ch;
;         const bf16_t* pp = last ? side + (size_t)(G * 4 + 2) * DFF2 + ch : side + (size_t)((G - 1) * 4 + 3) * DFF2 + ch;
;         const bf16_t* pn = last ? side + (size_t)((G + 1) * 4 + 0) * DFF2 + ch : side + (size_t)(G * 4 + 1) * DFF2 + ch;
;         u32x2 cv = *(const u32x2*)pc, cg = *(const u32x2*)(pc + DFF), pv = (u32x2){0u, 0u}, pg = pv, nv = pv, ng = pv;
;         if (hasp) { pv = *(const u32x2*)pp; pg = *(const u32x2*)(pp + DFF); }
;         if (hasn) { nv = *(const u32x2*)pn; ng = *(const u32x2*)(pn + DFF); }
;         const f32x4 kv0 = *(const f32x4*)(fk + ch), kv1 = *(const f32x4*)(fk + DFF2 + ch), kv2 = *(const f32x4*)(fk + 2 * DFF2 + ch), bv = *(const f32x4*)(fb + ch);
;         const f32x4 kg0 = *(const f32x4*)(fk + DFF + ch), kg1 = *(const f32x4*)(fk + DFF2 + DFF + ch), kg2 = *(const f32x4*)(fk + 2 * DFF2 + DFF + ch), bg = *(const f32x4*)(fb + DFF + ch);
;     ...
;         const f32x4 val = kv0 * UNP(pv) + kv1 * UNP(cv) + kv2 * UNP(nv) + bv, gt = kg0 * UNP(pg) + kg1 * UNP(cg) + kg2 * UNP(ng) + bg;
.Lgb_ld1:
	s_add_u32 s27, s27, s26
	s_mov_b32 s24, 0
	s_cmp_lt_u32 s27, s1
	s_cbranch_scc0 .Lgb_ld2
	s_mul_hi_u32 s31, s27, 0xba2e8ba3
	s_lshr_b32 s31, s31, 3
	s_mul_i32 s32, s31, 11
	s_sub_u32 s32, s27, s32
	s_and_b32 s34, s31, 1
	s_lshr_b32 s31, s31, 1
	s_lshl_b32 s38, s31, 6
	s_mul_i32 s40, s34, 63
	s_add_u32 s38, s38, s40
	s_lshl_b32 s41, s31, 2
	s_mul_i32 s40, s34, 3
	s_add_u32 s41, s41, s40
	s_lshl_b32 s32, s32, 9
	s_cmp_lt_u32 s38, 0x4000
	s_movk_i32 s42, 0x7ff
	s_movk_i32 s43, 0xff
	s_cselect_b32 s42, s42, s43
	s_and_b32 s43, s38, s42
	s_mov_b32 s24, 1
	s_cmp_lg_u32 s43, 0
	s_cselect_b32 s44, 2, 0
	s_or_b32 s24, s24, s44
	s_cmp_lg_u32 s43, s42
	s_cselect_b32 s44, 4, 0
	s_or_b32 s24, s24, s44
	s_mul_i32 s44, s38, 0x1600
	s_add_u32 s16, s36, s44
	s_addc_u32 s17, s37, 0
	s_add_u32 s16, s16, s32
	s_addc_u32 s17, s17, 0
	s_mul_i32 s44, s41, 0x2c00
	s_add_u32 s40, s45, s44
	s_addc_u32 s41, s46, 0
	s_add_u32 s40, s40, s32
	s_addc_u32 s41, s41, 0
	s_sub_u32 s42, s40, 0x2c00
	s_subb_u32 s43, s41, 0
	global_load_dwordx2 v[106:107], v1, s[40:41]
	global_load_dwordx2 v[108:109], v2, s[40:41]
	global_load_dwordx2 v[110:111], v1, s[42:43]
	global_load_dwordx2 v[112:113], v2, s[42:43]
	s_add_u32 s42, s40, 0x2c00
	s_addc_u32 s43, s41, 0
	global_load_dwordx2 v[114:115], v1, s[42:43]
	global_load_dwordx2 v[116:117], v2, s[42:43]
	s_lshl_b32 s32, s32, 1
	s_add_u32 s40, s8, s32
	s_addc_u32 s41, s9, 0
	s_add_u32 s42, s10, s32
	s_addc_u32 s43, s11, 0
	global_load_dwordx4 v[118:121], v3, s[40:41]
	global_load_dwordx4 v[122:125], v4, s[40:41]
	global_load_dwordx4 v[126:129], v5, s[40:41]
	global_load_dwordx4 v[130:133], v6, s[40:41]
	global_load_dwordx4 v[134:137], v7, s[40:41]
	global_load_dwordx4 v[138:141], v8, s[40:41]
	global_load_dwordx4 v[142:145], v3, s[42:43]
	global_load_dwordx4 v[146:149], v4, s[42:43]
.Lgb_ld2:
	s_add_u32 s27, s27, s26
	s_mov_b32 s25, 0
	s_cmp_lt_u32 s27, s1
	s_cbranch_scc0 .Lgb_ld3
	s_mul_hi_u32 s31, s27, 0xba2e8ba3
	s_lshr_b32 s31, s31, 3
	s_mul_i32 s32, s31, 11
	s_sub_u32 s32, s27, s32
	s_and_b32 s34, s31, 1
	s_lshr_b32 s31, s31, 1
	s_lshl_b32 s38, s31, 6
	s_mul_i32 s40, s34, 63
	s_add_u32 s38, s38, s40
	s_lshl_b32 s41, s31, 2
	s_mul_i32 s40, s34, 3
	s_add_u32 s41, s41, s40
	s_lshl_b32 s32, s32, 9
	s_cmp_lt_u32 s38, 0x4000
	s_movk_i32 s42, 0x7ff
	s_movk_i32 s43, 0xff
	s_cselect_b32 s42, s42, s43
	s_and_b32 s43, s38, s42
	s_mov_b32 s25, 1
	s_cmp_lg_u32 s43, 0
	s_cselect_b32 s44, 2, 0
	s_or_b32 s25, s25, s44
	s_cmp_lg_u32 s43, s42
	s_cselect_b32 s44, 4, 0
	s_or_b32 s25, s25, s44
	s_mul_i32 s44, s38, 0x1600
	s_add_u32 s68, s36, s44
	s_addc_u32 s69, s37, 0
	s_add_u32 s68, s68, s32
	s_addc_u32 s69, s69, 0
	s_mul_i32 s44, s41, 0x2c00
	s_add_u32 s40, s45, s44
	s_addc_u32 s41, s46, 0
	s_add_u32 s40, s40, s32
	s_addc_u32 s41, s41, 0
	s_sub_u32 s42, s40, 0x2c00
	s_subb_u32 s43, s41, 0
	global_load_dwordx2 v[150:151], v1, s[40:41]
	global_load_dwordx2 v[152:153], v2, s[40:41]
	global_load_dwordx2 v[160:161], v1, s[42:43]
	global_load_dwordx2 v[162:163], v2, s[42:43]
	s_add_u32 s42, s40, 0x2c00
	s_addc_u32 s43, s41, 0
	global_load_dwordx2 v[164:165], v1, s[42:43]
	global_load_dwordx2 v[166:167], v2, s[42:43]
	s_lshl_b32 s32, s32, 1
	s_add_u32 s40, s8, s32
	s_addc_u32 s41, s9, 0
	s_add_u32 s42, s10, s32
	s_addc_u32 s43, s11, 0
	global_load_dwordx4 v[168:171], v3, s[40:41]
	global_load_dwordx4 v[172:175], v4, s[40:41]
	global_load_dwordx4 v[176:179], v5, s[40:41]
	global_load_dwordx4 v[180:183], v6, s[40:41]
	global_load_dwordx4 v[184:187], v7, s[40:41]
	global_load_dwordx4 v[188:191], v8, s[40:41]
	global_load_dwordx4 v[192:195], v3, s[42:43]
	global_load_dwordx4 v[204:207], v4, s[42:43]
.Lgb_ld3:
	s_add_u32 s27, s27, s26
	s_waitcnt vmcnt(0)
	s_bitcmp1_b32 s22, 0
	s_cbranch_scc0 .Lgb_done0
	v_lshlrev_b32_e32 v208, 16, v16
	v_and_b32_e32 v209, s3, v16
	v_lshlrev_b32_e32 v210, 16, v17
	v_and_b32_e32 v211, s3, v17
	v_pk_mul_f32 v[226:227], v[36:37], v[208:209]
	v_pk_mul_f32 v[228:229], v[38:39], v[210:211]
	s_bitcmp1_b32 s22, 1
	s_cbranch_scc0 .Lgb_np0_0
	v_lshlrev_b32_e32 v212, 16, v20
	v_and_b32_e32 v213, s3, v20
	v_lshlrev_b32_e32 v214, 16, v21
	v_and_b32_e32 v215, s3, v21
	v_pk_fma_f32 v[226:227], v[28:29], v[212:213], v[226:227]
	v_pk_fma_f32 v[228:229], v[30:31], v[214:215], v[228:229]
.Lgb_np0_0:
	s_bitcmp1_b32 s22, 2
	s_cbranch_scc0 .Lgb_nn0_0
	v_lshlrev_b32_e32 v208, 16, v24
	v_and_b32_e32 v209, s3, v24
	v_lshlrev_b32_e32 v210, 16, v25
	v_and_b32_e32 v211, s3, v25
	v_pk_fma_f32 v[226:227], v[44:45], v[208:209], v[226:227]
	v_pk_fma_f32 v[228:229], v[46:47], v[210:211], v[228:229]
.Lgb_nn0_0:
	v_pk_add_f32 v[226:227], v[52:53], v[226:227]
	v_pk_add_f32 v[228:229], v[54:55], v[228:229]
	v_lshlrev_b32_e32 v208, 16, v18
	v_and_b32_e32 v209, s3, v18
	v_lshlrev_b32_e32 v210, 16, v19
	v_and_b32_e32 v211, s3, v19
	v_pk_mul_f32 v[230:231], v[40:41], v[208:209]
	v_pk_mul_f32 v[232:233], v[42:43], v[210:211]
	s_bitcmp1_b32 s22, 1
	s_cbranch_scc0 .Lgb_np0_1
	v_lshlrev_b32_e32 v212, 16, v22
	v_and_b32_e32 v213, s3, v22
	v_lshlrev_b32_e32 v214, 16, v23
	v_and_b32_e32 v215, s3, v23
	v_pk_fma_f32 v[230:231], v[32:33], v[212:213], v[230:231]
	v_pk_fma_f32 v[232:233], v[34:35], v[214:215], v[232:233]
.Lgb_np0_1:
	s_bitcmp1_b32 s22, 2
	s_cbranch_scc0 .Lgb_nn0_1
	v_lshlrev_b32_e32 v208, 16, v26
	v_and_b32_e32 v209, s3, v26
	v_lshlrev_b32_e32 v210, 16, v27
	v_and_b32_e32 v211, s3, v27
	v_pk_fma_f32 v[230:231], v[48:49], v[208:209], v[230:231]
	v_pk_fma_f32 v[232:233], v[50:51], v[210:211], v[232:233]
; __device__ __forceinline__ unsigned cvt_pk_bf16(float lo, float hi) { unsigned r; asm volatile("v_cvt_pk_bf16_f32 %0, %1, %2" : "=v"(r) : "v"(lo), "v"(hi)); return r; }
; __device__ __forceinline__ float silu_f(float x) { return x * __builtin_amdgcn_rcpf(1.0f + __builtin_amdgcn_exp2f(x * -1.4426950408889634f)); }
; #define UNP(w) (f32x4){bflo((w).x), bfhi((w).x), bflo((w).y), bfhi((w).y)}
; __device__ __forceinline__ void ffngate_fix(bf16_t* A2, const bf16_t* side, int rows, const float* fk, const float* fb, int gw, int NGW, int lane) {
;     ...
;         const f32x4 val = kv0 * UNP(pv) + kv1 * UNP(cv) + kv2 * UNP(nv) + bv, gt = kg0 * UNP(pg) + kg1 * UNP(cg) + kg2 * UNP(ng) + bg;
;     ...
;         u32x2 w; w.x = cvt_pk_bf16(silu_f(gt[0]) * val[0], silu_f(gt[1]) * val[1]); w.y = cvt_pk_bf16(silu_f(gt[2]) * val[2], silu_f(gt[3]) * val[3]);
;         *(u32x2*)(A2 + (size_t)R * DFF + ch) = w;
.Lgb_nn0_1:
	v_pk_add_f32 v[230:231], v[56:57], v[230:231]
	v_pk_add_f32 v[232:233], v[58:59], v[232:233]
	v_mul_f32_e32 v208, 0xbfb8aa3b, v230
	v_mul_f32_e32 v209, 0xbfb8aa3b, v231
	v_mul_f32_e32 v210, 0xbfb8aa3b, v232
	v_mul_f32_e32 v211, 0xbfb8aa3b, v233
	v_exp_f32_e32 v208, v208
	v_exp_f32_e32 v209, v209
	v_exp_f32_e32 v210, v210
	v_exp_f32_e32 v211, v211
	s_nop 0
	v_add_f32_e32 v208, 1.0, v208
	v_add_f32_e32 v209, 1.0, v209
	v_add_f32_e32 v210, 1.0, v210
	v_add_f32_e32 v211, 1.0, v211
	v_rcp_f32_e32 v208, v208
	v_rcp_f32_e32 v209, v209
	v_rcp_f32_e32 v210, v210
	v_rcp_f32_e32 v211, v211
	s_nop 0
	v_mul_f32_e32 v208, v230, v208
	v_mul_f32_e32 v209, v231, v209
	v_mul_f32_e32 v210, v232, v210
	v_mul_f32_e32 v211, v233, v211
	v_mul_f32_e32 v208, v226, v208
	v_mul_f32_e32 v209, v227, v209
	v_mul_f32_e32 v210, v228, v210
	v_mul_f32_e32 v211, v229, v211
	v_cvt_pk_bf16_f32 v234, v208, v209
	v_cvt_pk_bf16_f32 v235, v210, v211
	global_store_dwordx2 v1, v[234:235], s[12:13]
.Lgb_done0:
	s_bitcmp1_b32 s23, 0
	s_cbranch_scc0 .Lgb_done1
	v_lshlrev_b32_e32 v208, 16, v60
	v_and_b32_e32 v209, s3, v60
	v_lshlrev_b32_e32 v210, 16, v61
	v_and_b32_e32 v211, s3, v61
	v_pk_mul_f32 v[226:227], v[80:81], v[208:209]
	v_pk_mul_f32 v[228:229], v[82:83], v[210:211]
	s_bitcmp1_b32 s23, 1
	s_cbranch_scc0 .Lgb_np1_0
	v_lshlrev_b32_e32 v212, 16, v64
	v_and_b32_e32 v213, s3, v64
	v_lshlrev_b32_e32 v214, 16, v65
	v_and_b32_e32 v215, s3, v65
	v_pk_fma_f32 v[226:227], v[72:73], v[212:213], v[226:227]
	v_pk_fma_f32 v[228:229], v[74:75], v[214:215], v[228:229]
.Lgb_np1_0:
	s_bitcmp1_b32 s23, 2
	s_cbranch_scc0 .Lgb_nn1_0
	v_lshlrev_b32_e32 v208, 16, v68
	v_and_b32_e32 v209, s3, v68
	v_lshlrev_b32_e32 v210, 16, v69
	v_and_b32_e32 v211, s3, v69
	v_pk_fma_f32 v[226:227], v[88:89], v[208:209], v[226:227]
	v_pk_fma_f32 v[228:229], v[90:91], v[210:211], v[228:229]
.Lgb_nn1_0:
	v_pk_add_f32 v[226:227], v[98:99], v[226:227]
	v_pk_add_f32 v[228:229], v[100:101], v[228:229]
	v_lshlrev_b32_e32 v208, 16, v62
	v_and_b32_e32 v209, s3, v62
	v_lshlrev_b32_e32 v210, 16, v63
	v_and_b32_e32 v211, s3, v63
	v_pk_mul_f32 v[230:231], v[84:85], v[208:209]
	v_pk_mul_f32 v[232:233], v[86:87], v[210:211]
	s_bitcmp1_b32 s23, 1
	s_cbranch_scc0 .Lgb_np1_1
	v_lshlrev_b32_e32 v212, 16, v66
	v_and_b32_e32 v213, s3, v66
	v_lshlrev_b32_e32 v214, 16, v67
	v_and_b32_e32 v215, s3, v67
	v_pk_fma_f32 v[230:231], v[76:77], v[212:213], v[230:231]
	v_pk_fma_f32 v[232:233], v[78:79], v[214:215], v[232:233]
.Lgb_np1_1:
	s_bitcmp1_b32 s23, 2
	s_cbranch_scc0 .Lgb_nn1_1
	v_lshlrev_b32_e32 v208, 16, v70
	v_and_b32_e32 v209, s3, v70
	v_lshlrev_b32_e32 v210, 16, v71
	v_and_b32_e32 v211, s3, v71
	v_pk_fma_f32 v[230:231], v[92:93], v[208:209], v[230:231]
	v_pk_fma_f32 v[232:233], v[94:95], v[210:211], v[232:233]
.Lgb_nn1_1:
	v_pk_add_f32 v[230:231], v[102:103], v[230:231]
	v_pk_add_f32 v[232:233], v[104:105], v[232:233]
	v_mul_f32_e32 v208, 0xbfb8aa3b, v230
	v_mul_f32_e32 v209, 0xbfb8aa3b, v231
	v_mul_f32_e32 v210, 0xbfb8aa3b, v232
	v_mul_f32_e32 v211, 0xbfb8aa3b, v233
	v_exp_f32_e32 v208, v208
	v_exp_f32_e32 v209, v209
	v_exp_f32_e32 v210, v210
	v_exp_f32_e32 v211, v211
	s_nop 0
	v_add_f32_e32 v208, 1.0, v208
	v_add_f32_e32 v209, 1.0, v209
	v_add_f32_e32 v210, 1.0, v210
	v_add_f32_e32 v211, 1.0, v211
	v_rcp_f32_e32 v208, v208
	v_rcp_f32_e32 v209, v209
	v_rcp_f32_e32 v210, v210
	v_rcp_f32_e32 v211, v211
	s_nop 0
	v_mul_f32_e32 v208, v230, v208
	v_mul_f32_e32 v209, v231, v209
	v_mul_f32_e32 v210, v232, v210
	v_mul_f32_e32 v211, v233, v211
	v_mul_f32_e32 v208, v226, v208
	v_mul_f32_e32 v209, v227, v209
	v_mul_f32_e32 v210, v228, v210
	v_mul_f32_e32 v211, v229, v211
	v_cvt_pk_bf16_f32 v234, v208, v209
	v_cvt_pk_bf16_f32 v235, v210, v211
	global_store_dwordx2 v1, v[234:235], s[14:15]
.Lgb_done1:
	s_bitcmp1_b32 s24, 0
	s_cbranch_scc0 .Lgb_done2
	v_lshlrev_b32_e32 v208, 16, v106
	v_and_b32_e32 v209, s3, v106
	v_lshlrev_b32_e32 v210, 16, v107
	v_and_b32_e32 v211, s3, v107
	v_pk_mul_f32 v[226:227], v[126:127], v[208:209]
	v_pk_mul_f32 v[228:229], v[128:129], v[210:211]
	s_bitcmp1_b32 s24, 1
	s_cbranch_scc0 .Lgb_np2_0
	v_lshlrev_b32_e32 v212, 16, v110
	v_and_b32_e32 v213, s3, v110
	v_lshlrev_b32_e32 v214, 16, v111
	v_and_b32_e32 v215, s3, v111
	v_pk_fma_f32 v[226:227], v[118:119], v[212:213], v[226:227]
	v_pk_fma_f32 v[228:229], v[120:121], v[214:215], v[228:229]
.Lgb_np2_0:
	s_bitcmp1_b32 s24, 2
	s_cbranch_scc0 .Lgb_nn2_0
	v_lshlrev_b32_e32 v208, 16, v114
	v_and_b32_e32 v209, s3, v114
	v_lshlrev_b32_e32 v210, 16, v115
	v_and_b32_e32 v211, s3, v115
	v_pk_fma_f32 v[226:227], v[134:135], v[208:209], v[226:227]
	v_pk_fma_f32 v[228:229], v[136:137], v[210:211], v[228:229]
; __device__ __forceinline__ unsigned cvt_pk_bf16(float lo, float hi) { unsigned r; asm volatile("v_cvt_pk_bf16_f32 %0, %1, %2" : "=v"(r) : "v"(lo), "v"(hi)); return r; }
; __device__ __forceinline__ float silu_f(float x) { return x * __builtin_amdgcn_rcpf(1.0f + __builtin_amdgcn_exp2f(x * -1.4426950408889634f)); }
; #define UNP(w) (f32x4){bflo((w).x), bfhi((w).x), bflo((w).y), bfhi((w).y)}
; __device__ __forceinline__ void ffngate_fix(bf16_t* A2, const bf16_t* side, int rows, const float* fk, const float* fb, int gw, int NGW, int lane) {
;     ...
;         const f32x4 val = kv0 * UNP(pv) + kv1 * UNP(cv) + kv2 * UNP(nv) + bv, gt = kg0 * UNP(pg) + kg1 * UNP(cg) + kg2 * UNP(ng) + bg;
;     ...
;         u32x2 w; w.x = cvt_pk_bf16(silu_f(gt[0]) * val[0], silu_f(gt[1]) * val[1]); w.y = cvt_pk_bf16(silu_f(gt[2]) * val[2], silu_f(gt[3]) * val[3]);
;         *(u32x2*)(A2 + (size_t)R * DFF + ch) = w;
.Lgb_nn2_0:
	v_pk_add_f32 v[226:227], v[142:143], v[226:227]
	v_pk_add_f32 v[228:229], v[144:145], v[228:229]
	v_lshlrev_b32_e32 v208, 16, v108
	v_and_b32_e32 v209, s3, v108
	v_lshlrev_b32_e32 v210, 16, v109
	v_and_b32_e32 v211, s3, v109
	v_pk_mul_f32 v[230:231], v[130:131], v[208:209]
	v_pk_mul_f32 v[232:233], v[132:133], v[210:211]
	s_bitcmp1_b32 s24, 1
	s_cbranch_scc0 .Lgb_np2_1
	v_lshlrev_b32_e32 v212, 16, v112
	v_and_b32_e32 v213, s3, v112
	v_lshlrev_b32_e32 v214, 16, v113
	v_and_b32_e32 v215, s3, v113
	v_pk_fma_f32 v[230:231], v[122:123], v[212:213], v[230:231]
	v_pk_fma_f32 v[232:233], v[124:125], v[214:215], v[232:233]
.Lgb_np2_1:
	s_bitcmp1_b32 s24, 2
	s_cbranch_scc0 .Lgb_nn2_1
	v_lshlrev_b32_e32 v208, 16, v116
	v_and_b32_e32 v209, s3, v116
	v_lshlrev_b32_e32 v210, 16, v117
	v_and_b32_e32 v211, s3, v117
	v_pk_fma_f32 v[230:231], v[138:139], v[208:209], v[230:231]
	v_pk_fma_f32 v[232:233], v[140:141], v[210:211], v[232:233]
.Lgb_nn2_1:
	v_pk_add_f32 v[230:231], v[146:147], v[230:231]
	v_pk_add_f32 v[232:233], v[148:149], v[232:233]
	v_mul_f32_e32 v208, 0xbfb8aa3b, v230
	v_mul_f32_e32 v209, 0xbfb8aa3b, v231
	v_mul_f32_e32 v210, 0xbfb8aa3b, v232
	v_mul_f32_e32 v211, 0xbfb8aa3b, v233
	v_exp_f32_e32 v208, v208
	v_exp_f32_e32 v209, v209
	v_exp_f32_e32 v210, v210
	v_exp_f32_e32 v211, v211
	s_nop 0
	v_add_f32_e32 v208, 1.0, v208
	v_add_f32_e32 v209, 1.0, v209
	v_add_f32_e32 v210, 1.0, v210
	v_add_f32_e32 v211, 1.0, v211
	v_rcp_f32_e32 v208, v208
	v_rcp_f32_e32 v209, v209
	v_rcp_f32_e32 v210, v210
	v_rcp_f32_e32 v211, v211
	s_nop 0
	v_mul_f32_e32 v208, v230, v208
	v_mul_f32_e32 v209, v231, v209
	v_mul_f32_e32 v210, v232, v210
	v_mul_f32_e32 v211, v233, v211
	v_mul_f32_e32 v208, v226, v208
	v_mul_f32_e32 v209, v227, v209
	v_mul_f32_e32 v210, v228, v210
	v_mul_f32_e32 v211, v229, v211
	v_cvt_pk_bf16_f32 v234, v208, v209
	v_cvt_pk_bf16_f32 v235, v210, v211
	global_store_dwordx2 v1, v[234:235], s[16:17]
.Lgb_done2:
	s_bitcmp1_b32 s25, 0
	s_cbranch_scc0 .Lgb_done3
	v_lshlrev_b32_e32 v208, 16, v150
	v_and_b32_e32 v209, s3, v150
	v_lshlrev_b32_e32 v210, 16, v151
	v_and_b32_e32 v211, s3, v151
	v_pk_mul_f32 v[226:227], v[176:177], v[208:209]
	v_pk_mul_f32 v[228:229], v[178:179], v[210:211]
	s_bitcmp1_b32 s25, 1
	s_cbranch_scc0 .Lgb_np3_0
	v_lshlrev_b32_e32 v212, 16, v160
	v_and_b32_e32 v213, s3, v160
	v_lshlrev_b32_e32 v214, 16, v161
	v_and_b32_e32 v215, s3, v161
	v_pk_fma_f32 v[226:227], v[168:169], v[212:213], v[226:227]
	v_pk_fma_f32 v[228:229], v[170:171], v[214:215], v[228:229]
.Lgb_np3_0:
	s_bitcmp1_b32 s25, 2
	s_cbranch_scc0 .Lgb_nn3_0
	v_lshlrev_b32_e32 v208, 16, v164
	v_and_b32_e32 v209, s3, v164
	v_lshlrev_b32_e32 v210, 16, v165
	v_and_b32_e32 v211, s3, v165
	v_pk_fma_f32 v[226:227], v[184:185], v[208:209], v[226:227]
	v_pk_fma_f32 v[228:229], v[186:187], v[210:211], v[228:229]
.Lgb_nn3_0:
	v_pk_add_f32 v[226:227], v[192:193], v[226:227]
	v_pk_add_f32 v[228:229], v[194:195], v[228:229]
	v_lshlrev_b32_e32 v208, 16, v152
	v_and_b32_e32 v209, s3, v152
	v_lshlrev_b32_e32 v210, 16, v153
	v_and_b32_e32 v211, s3, v153
	v_pk_mul_f32 v[230:231], v[180:181], v[208:209]
	v_pk_mul_f32 v[232:233], v[182:183], v[210:211]
	s_bitcmp1_b32 s25, 1
	s_cbranch_scc0 .Lgb_np3_1
	v_lshlrev_b32_e32 v212, 16, v162
	v_and_b32_e32 v213, s3, v162
	v_lshlrev_b32_e32 v214, 16, v163
	v_and_b32_e32 v215, s3, v163
	v_pk_fma_f32 v[230:231], v[172:173], v[212:213], v[230:231]
	v_pk_fma_f32 v[232:233], v[174:175], v[214:215], v[232:233]
.Lgb_np3_1:
	s_bitcmp1_b32 s25, 2
	s_cbranch_scc0 .Lgb_nn3_1
	v_lshlrev_b32_e32 v208, 16, v166
	v_and_b32_e32 v209, s3, v166
	v_lshlrev_b32_e32 v210, 16, v167
	v_and_b32_e32 v211, s3, v167
	v_pk_fma_f32 v[230:231], v[188:189], v[208:209], v[230:231]
	v_pk_fma_f32 v[232:233], v[190:191], v[210:211], v[232:233]
.Lgb_nn3_1:
	v_pk_add_f32 v[230:231], v[204:205], v[230:231]
	v_pk_add_f32 v[232:233], v[206:207], v[232:233]
	v_mul_f32_e32 v208, 0xbfb8aa3b, v230
	v_mul_f32_e32 v209, 0xbfb8aa3b, v231
	v_mul_f32_e32 v210, 0xbfb8aa3b, v232
	v_mul_f32_e32 v211, 0xbfb8aa3b, v233
	v_exp_f32_e32 v208, v208
	v_exp_f32_e32 v209, v209
	v_exp_f32_e32 v210, v210
	v_exp_f32_e32 v211, v211
	s_nop 0
	v_add_f32_e32 v208, 1.0, v208
	v_add_f32_e32 v209, 1.0, v209
	v_add_f32_e32 v210, 1.0, v210
	v_add_f32_e32 v211, 1.0, v211
	v_rcp_f32_e32 v208, v208
	v_rcp_f32_e32 v209, v209
	v_rcp_f32_e32 v210, v210
	v_rcp_f32_e32 v211, v211
	s_nop 0
	v_mul_f32_e32 v208, v230, v208
	v_mul_f32_e32 v209, v231, v209
	v_mul_f32_e32 v210, v232, v210
	v_mul_f32_e32 v211, v233, v211
	v_mul_f32_e32 v208, v226, v208
	v_mul_f32_e32 v209, v227, v209
	v_mul_f32_e32 v210, v228, v210
	v_mul_f32_e32 v211, v229, v211
	v_cvt_pk_bf16_f32 v234, v208, v209
	v_cvt_pk_bf16_f32 v235, v210, v211
	global_store_dwordx2 v1, v[234:235], s[68:69]
.Lgb_done3:
	s_branch .LBB0_132
.LBB0_125:
	v_readlane_b32 s86, v254, 28
	v_readlane_b32 s87, v254, 29
	s_getpc_b64 s[98:99]
.Lpost_getpc0:
	s_add_u32 s98, s98, (.LBB0_1168-.Lpost_getpc0)&4294967295
	s_addc_u32 s99, s99, (.LBB0_1168-.Lpost_getpc0)>>32
	s_setpc_b64 s[98:99]
.LBB0_132:
	s_mov_b64 s[8:9], 0
